# out-proj drain epilogue: per-row waits count the three stores of earlier rows (in-order vmcnt) instead of assuming none, when all three outputs are enabled
# baseline (speedup 1.0000x reference)
.LBB0_461:
	v_cndmask_b32_e64 v64, 0, 1, s[42:43]
	s_and_b64 vcc, exec, s[8:9]
	v_cmp_ne_u32_e64 s[8:9], 1, v64
	s_cbranch_vccz .LBB0_410
	s_mov_b32 s98, 0
	s_cmp_lg_u64 s[8:9], 0
	s_cbranch_scc1 .Ldrmode_a
	s_cmp_eq_u64 s[2:3], 0
	s_cbranch_scc1 .Ldrmode_a
	s_cmp_eq_u64 s[40:41], 0
	s_cbranch_scc1 .Ldrmode_a
	s_mov_b32 s98, 2
.Ldrmode_a:
	v_lshl_add_u64 v[64:65], v[98:99], 2, s[68:69]
	v_add_co_u32_e32 v66, vcc, 0x10000, v64
	v_add_u32_e32 v100, s12, v110
	s_nop 0
	v_addc_co_u32_e32 v67, vcc, 0, v65, vcc
	global_load_dwordx4 v[92:95], v[64:65], off
	global_load_dwordx4 v[88:91], v[66:67], off
	v_add_co_u32_e32 v66, vcc, 0x20000, v64
	s_nop 1
	v_addc_co_u32_e32 v67, vcc, 0, v65, vcc
	v_add_co_u32_e32 v68, vcc, 0x30000, v64
	s_nop 1
	v_addc_co_u32_e32 v69, vcc, 0, v65, vcc
	global_load_dwordx4 v[84:87], v[66:67], off
	global_load_dwordx4 v[80:83], v[68:69], off
	v_add_co_u32_e32 v66, vcc, 0x40000, v64
	s_nop 1
	v_addc_co_u32_e32 v67, vcc, 0, v65, vcc
	v_add_co_u32_e32 v68, vcc, 0x50000, v64
	s_nop 1
	v_addc_co_u32_e32 v69, vcc, 0, v65, vcc
	global_load_dwordx4 v[76:79], v[66:67], off
	global_load_dwordx4 v[72:75], v[68:69], off
	v_add_co_u32_e32 v66, vcc, 0x60000, v64
	s_nop 1
	v_addc_co_u32_e32 v67, vcc, 0, v65, vcc
	v_add_co_u32_e32 v64, vcc, 0x70000, v64
	s_nop 1
	v_addc_co_u32_e32 v65, vcc, 0, v65, vcc
	global_load_dwordx4 v[68:71], v[66:67], off
	s_nop 0
	global_load_dwordx4 v[64:67], v[64:65], off
	ds_read_b128 v[102:105], v100
	s_cmp_eq_u32 s98, 2
	s_cbranch_scc0 .Ldrw_a0_n
	s_waitcnt vmcnt(7)
	s_branch .Ldrw_a0_e

.Ldrw_a0_e:
	s_and_b64 vcc, exec, s[8:9]
	s_waitcnt lgkmcnt(0)
	v_pk_add_f32 v[94:95], v[94:95], v[104:105]
	v_pk_add_f32 v[92:93], v[92:93], v[102:103]
	s_cbranch_vccnz .LBB0_464
	v_lshlrev_b32_e32 v101, 2, v98
	buffer_store_dwordx4 v[92:95], v101, s[16:19], 0 offen sc1

.LBB0_470:
	ds_read_b128 v[92:95], v100 offset:8320
	s_mov_b64 s[46:47], 0x4000
	s_cmp_eq_u32 s98, 2
	s_cbranch_scc0 .Ldrw_a1_n
	s_waitcnt vmcnt(9)
	s_branch .Ldrw_a1_e

.Ldrw_a1_e:
	s_and_b64 vcc, exec, s[8:9]
	s_waitcnt lgkmcnt(0)
	v_pk_add_f32 v[88:89], v[88:89], v[92:93]
	v_pk_add_f32 v[90:91], v[90:91], v[94:95]
	v_lshl_add_u64 v[92:93], v[98:99], 0, s[46:47]
	s_cbranch_vccnz .LBB0_472
	v_lshlrev_b32_e32 v94, 2, v92
	buffer_store_dwordx4 v[88:91], v94, s[16:19], 0 offen sc1

.LBB0_478:
	ds_read_b128 v[88:91], v100 offset:16640
	s_mov_b64 s[46:47], 0x8000
	s_cmp_eq_u32 s98, 2
	s_cbranch_scc0 .Ldrw_a2_n
	s_waitcnt vmcnt(11)
	s_branch .Ldrw_a2_e
.Ldrw_a2_n:
	s_waitcnt vmcnt(5)
.Ldrw_a2_e:
	s_and_b64 vcc, exec, s[8:9]
	s_waitcnt lgkmcnt(0)
	v_pk_add_f32 v[84:85], v[84:85], v[88:89]
	v_pk_add_f32 v[86:87], v[86:87], v[90:91]
	v_lshl_add_u64 v[88:89], v[98:99], 0, s[46:47]
	s_cbranch_vccnz .LBB0_480
	v_lshlrev_b32_e32 v90, 2, v88
	buffer_store_dwordx4 v[84:87], v90, s[16:19], 0 offen sc1

.LBB0_486:
	ds_read_b128 v[84:87], v100 offset:24960
	s_mov_b64 s[46:47], 0xc000
	s_cmp_eq_u32 s98, 2
	s_cbranch_scc0 .Ldrw_a3_n
	s_waitcnt vmcnt(13)
	s_branch .Ldrw_a3_e
.Ldrw_a3_n:
	s_waitcnt vmcnt(4)
.Ldrw_a3_e:
	s_and_b64 vcc, exec, s[8:9]
	s_waitcnt lgkmcnt(0)
	v_pk_add_f32 v[80:81], v[80:81], v[84:85]
	v_pk_add_f32 v[82:83], v[82:83], v[86:87]
	v_lshl_add_u64 v[84:85], v[98:99], 0, s[46:47]
	s_cbranch_vccnz .LBB0_488
	v_lshlrev_b32_e32 v86, 2, v84
	buffer_store_dwordx4 v[80:83], v86, s[16:19], 0 offen sc1

.LBB0_494:
	ds_read_b128 v[80:83], v100 offset:33280
	s_mov_b64 s[46:47], 0x10000
	s_cmp_eq_u32 s98, 2
	s_cbranch_scc0 .Ldrw_a4_n
	s_waitcnt vmcnt(15)
	s_branch .Ldrw_a4_e

.Ldrw_a4_e:
	s_and_b64 vcc, exec, s[8:9]
	s_waitcnt lgkmcnt(0)
	v_pk_add_f32 v[76:77], v[76:77], v[80:81]
	v_pk_add_f32 v[78:79], v[78:79], v[82:83]
	v_lshl_add_u64 v[80:81], v[98:99], 0, s[46:47]
	s_cbranch_vccnz .LBB0_496
	v_lshlrev_b32_e32 v82, 2, v80
	buffer_store_dwordx4 v[76:79], v82, s[16:19], 0 offen sc1

.LBB0_502:
	ds_read_b128 v[76:79], v100 offset:41600
	s_mov_b64 s[46:47], 0x14000
	s_cmp_eq_u32 s98, 2
	s_cbranch_scc0 .Ldrw_a5_n
	s_waitcnt vmcnt(17)
	s_branch .Ldrw_a5_e
.Ldrw_a5_n:
	s_waitcnt vmcnt(2)
.Ldrw_a5_e:
	s_and_b64 vcc, exec, s[8:9]
	s_waitcnt lgkmcnt(0)
	v_pk_add_f32 v[72:73], v[72:73], v[76:77]
	v_pk_add_f32 v[74:75], v[74:75], v[78:79]
	v_lshl_add_u64 v[76:77], v[98:99], 0, s[46:47]
	s_cbranch_vccnz .LBB0_504
	v_lshlrev_b32_e32 v78, 2, v76
	buffer_store_dwordx4 v[72:75], v78, s[16:19], 0 offen sc1

.LBB0_510:
	ds_read_b128 v[72:75], v100 offset:49920
	s_mov_b64 s[46:47], 0x18000
	s_cmp_eq_u32 s98, 2
	s_cbranch_scc0 .Ldrw_a6_n
	s_waitcnt vmcnt(19)
	s_branch .Ldrw_a6_e
.Ldrw_a6_n:
	s_waitcnt vmcnt(1)
.Ldrw_a6_e:
	s_and_b64 vcc, exec, s[8:9]
	s_waitcnt lgkmcnt(0)
	v_pk_add_f32 v[68:69], v[68:69], v[72:73]
	v_pk_add_f32 v[70:71], v[70:71], v[74:75]
	v_lshl_add_u64 v[72:73], v[98:99], 0, s[46:47]
	s_cbranch_vccnz .LBB0_512
	v_lshlrev_b32_e32 v74, 2, v72
	buffer_store_dwordx4 v[68:71], v74, s[16:19], 0 offen sc1

.LBB0_518:
	ds_read_b128 v[68:71], v100 offset:58240
	s_mov_b64 s[46:47], 0x1c000
	s_cmp_eq_u32 s98, 2
	s_cbranch_scc0 .Ldrw_a7_n
	s_waitcnt vmcnt(21)
	s_branch .Ldrw_a7_e

.Ldrw_a7_e:
	s_and_b64 vcc, exec, s[8:9]
	s_waitcnt lgkmcnt(0)
	v_pk_add_f32 v[66:67], v[66:67], v[70:71]
	v_pk_add_f32 v[64:65], v[64:65], v[68:69]
	v_lshl_add_u64 v[68:69], v[98:99], 0, s[46:47]
	s_cbranch_vccnz .LBB0_520
	v_lshlrev_b32_e32 v70, 2, v68
	buffer_store_dwordx4 v[64:67], v70, s[16:19], 0 offen sc1

.LBB0_578:
	s_and_b64 vcc, exec, s[10:11]
	s_cbranch_vccz .LBB0_527
	s_mov_b32 s98, 0
	s_cmp_lg_u64 s[8:9], 0
	s_cbranch_scc1 .Ldrmode_b
	s_cmp_eq_u64 s[2:3], 0
	s_cbranch_scc1 .Ldrmode_b
	s_cmp_eq_u64 s[40:41], 0
	s_cbranch_scc1 .Ldrmode_b
	s_mov_b32 s98, 2
.Ldrmode_b:
	v_lshl_add_u64 v[0:1], v[34:35], 2, s[68:69]
	v_add_co_u32_e32 v2, vcc, 0x10000, v0
	v_add_u32_e32 v36, s42, v110
	s_nop 0
	v_addc_co_u32_e32 v3, vcc, 0, v1, vcc
	global_load_dwordx4 v[28:31], v[0:1], off
	global_load_dwordx4 v[24:27], v[2:3], off
	v_add_co_u32_e32 v2, vcc, 0x20000, v0
	s_nop 1
	v_addc_co_u32_e32 v3, vcc, 0, v1, vcc
	v_add_co_u32_e32 v4, vcc, 0x30000, v0
	s_nop 1
	v_addc_co_u32_e32 v5, vcc, 0, v1, vcc
	global_load_dwordx4 v[20:23], v[2:3], off
	global_load_dwordx4 v[16:19], v[4:5], off
	v_add_co_u32_e32 v2, vcc, 0x40000, v0
	s_nop 1
	v_addc_co_u32_e32 v3, vcc, 0, v1, vcc
	v_add_co_u32_e32 v4, vcc, 0x50000, v0
	s_nop 1
	v_addc_co_u32_e32 v5, vcc, 0, v1, vcc
	global_load_dwordx4 v[12:15], v[2:3], off
	global_load_dwordx4 v[8:11], v[4:5], off
	v_add_co_u32_e32 v2, vcc, 0x60000, v0
	s_nop 1
	v_addc_co_u32_e32 v3, vcc, 0, v1, vcc
	v_add_co_u32_e32 v0, vcc, 0x70000, v0
	s_nop 1
	v_addc_co_u32_e32 v1, vcc, 0, v1, vcc
	global_load_dwordx4 v[4:7], v[2:3], off
	s_nop 0
	global_load_dwordx4 v[0:3], v[0:1], off
	ds_read_b128 v[38:41], v36
	s_cmp_eq_u32 s98, 2
	s_cbranch_scc0 .Ldrw_b0_n
	s_waitcnt vmcnt(7)
	s_branch .Ldrw_b0_e

.Ldrw_b0_e:
	s_and_b64 vcc, exec, s[8:9]
	s_waitcnt lgkmcnt(0)
	v_pk_add_f32 v[30:31], v[30:31], v[40:41]
	v_pk_add_f32 v[28:29], v[28:29], v[38:39]
	s_cbranch_vccnz .LBB0_581
	v_lshlrev_b32_e32 v37, 2, v34
	buffer_store_dwordx4 v[28:31], v37, s[16:19], 0 offen sc1

.LBB0_587:
	ds_read_b128 v[28:31], v36 offset:8320
	s_mov_b64 s[42:43], 0x4000
	s_cmp_eq_u32 s98, 2
	s_cbranch_scc0 .Ldrw_b1_n
	s_waitcnt vmcnt(9)
	s_branch .Ldrw_b1_e

.Ldrw_b1_e:
	s_and_b64 vcc, exec, s[8:9]
	s_waitcnt lgkmcnt(0)
	v_pk_add_f32 v[24:25], v[24:25], v[28:29]
	v_pk_add_f32 v[26:27], v[26:27], v[30:31]
	v_lshl_add_u64 v[28:29], v[34:35], 0, s[42:43]
	s_cbranch_vccnz .LBB0_589
	v_lshlrev_b32_e32 v30, 2, v28
	buffer_store_dwordx4 v[24:27], v30, s[16:19], 0 offen sc1

.LBB0_595:
	ds_read_b128 v[24:27], v36 offset:16640
	s_mov_b64 s[42:43], 0x8000
	s_cmp_eq_u32 s98, 2
	s_cbranch_scc0 .Ldrw_b2_n
	s_waitcnt vmcnt(11)
	s_branch .Ldrw_b2_e

.Ldrw_b2_e:
	s_and_b64 vcc, exec, s[8:9]
	s_waitcnt lgkmcnt(0)
	v_pk_add_f32 v[20:21], v[20:21], v[24:25]
	v_pk_add_f32 v[22:23], v[22:23], v[26:27]
	v_lshl_add_u64 v[24:25], v[34:35], 0, s[42:43]
	s_cbranch_vccnz .LBB0_597
	v_lshlrev_b32_e32 v26, 2, v24
	buffer_store_dwordx4 v[20:23], v26, s[16:19], 0 offen sc1

.LBB0_603:
	ds_read_b128 v[20:23], v36 offset:24960
	s_mov_b64 s[42:43], 0xc000
	s_cmp_eq_u32 s98, 2
	s_cbranch_scc0 .Ldrw_b3_n
	s_waitcnt vmcnt(13)
	s_branch .Ldrw_b3_e

.Ldrw_b3_e:
	s_and_b64 vcc, exec, s[8:9]
	s_waitcnt lgkmcnt(0)
	v_pk_add_f32 v[16:17], v[16:17], v[20:21]
	v_pk_add_f32 v[18:19], v[18:19], v[22:23]
	v_lshl_add_u64 v[20:21], v[34:35], 0, s[42:43]
	s_cbranch_vccnz .LBB0_605
	v_lshlrev_b32_e32 v22, 2, v20
	buffer_store_dwordx4 v[16:19], v22, s[16:19], 0 offen sc1

.LBB0_611:
	ds_read_b128 v[16:19], v36 offset:33280
	s_mov_b64 s[42:43], 0x10000
	s_cmp_eq_u32 s98, 2
	s_cbranch_scc0 .Ldrw_b4_n
	s_waitcnt vmcnt(15)
	s_branch .Ldrw_b4_e

.Ldrw_b4_e:
	s_and_b64 vcc, exec, s[8:9]
	s_waitcnt lgkmcnt(0)
	v_pk_add_f32 v[12:13], v[12:13], v[16:17]
	v_pk_add_f32 v[14:15], v[14:15], v[18:19]
	v_lshl_add_u64 v[16:17], v[34:35], 0, s[42:43]
	s_cbranch_vccnz .LBB0_613
	v_lshlrev_b32_e32 v18, 2, v16
	buffer_store_dwordx4 v[12:15], v18, s[16:19], 0 offen sc1

.LBB0_619:
	ds_read_b128 v[12:15], v36 offset:41600
	s_mov_b64 s[42:43], 0x14000
	s_cmp_eq_u32 s98, 2
	s_cbranch_scc0 .Ldrw_b5_n
	s_waitcnt vmcnt(17)
	s_branch .Ldrw_b5_e

.Ldrw_b5_e:
	s_and_b64 vcc, exec, s[8:9]
	s_waitcnt lgkmcnt(0)
	v_pk_add_f32 v[8:9], v[8:9], v[12:13]
	v_pk_add_f32 v[10:11], v[10:11], v[14:15]
	v_lshl_add_u64 v[12:13], v[34:35], 0, s[42:43]
	s_cbranch_vccnz .LBB0_621
	v_lshlrev_b32_e32 v14, 2, v12
	buffer_store_dwordx4 v[8:11], v14, s[16:19], 0 offen sc1

.LBB0_627:
	ds_read_b128 v[8:11], v36 offset:49920
	s_mov_b64 s[42:43], 0x18000
	s_cmp_eq_u32 s98, 2
	s_cbranch_scc0 .Ldrw_b6_n
	s_waitcnt vmcnt(19)
	s_branch .Ldrw_b6_e

.Ldrw_b6_e:
	s_and_b64 vcc, exec, s[8:9]
	s_waitcnt lgkmcnt(0)
	v_pk_add_f32 v[4:5], v[4:5], v[8:9]
	v_pk_add_f32 v[6:7], v[6:7], v[10:11]
	v_lshl_add_u64 v[8:9], v[34:35], 0, s[42:43]
	s_cbranch_vccnz .LBB0_629
	v_lshlrev_b32_e32 v10, 2, v8
	buffer_store_dwordx4 v[4:7], v10, s[16:19], 0 offen sc1

.LBB0_635:
	ds_read_b128 v[4:7], v36 offset:58240
	s_mov_b64 s[42:43], 0x1c000
	s_cmp_eq_u32 s98, 2
	s_cbranch_scc0 .Ldrw_b7_n
	s_waitcnt vmcnt(21)
	s_branch .Ldrw_b7_e

.Ldrw_b7_e:
	s_and_b64 vcc, exec, s[8:9]
	s_waitcnt lgkmcnt(0)
	v_pk_add_f32 v[2:3], v[2:3], v[6:7]
	v_pk_add_f32 v[0:1], v[0:1], v[4:5]
	v_lshl_add_u64 v[4:5], v[34:35], 0, s[42:43]
	s_cbranch_vccnz .LBB0_637
	v_lshlrev_b32_e32 v6, 2, v4
	buffer_store_dwordx4 v[0:3], v6, s[16:19], 0 offen sc1
